# grid-barrier seams: non-last workgroups issue their L1 invalidate on arrival (before polling) instead of after the release; the CU issues no cached loads in between
# speedup vs baseline: 1.0221x; 1.0117x over previous
; __device__ __forceinline__ unsigned xb_ld(unsigned* p)              { return __hip_atomic_load(p, __ATOMIC_RELAXED, __HIP_MEMORY_SCOPE_AGENT); }
; __device__ __forceinline__ unsigned xb_add(unsigned* p, unsigned v) { return __hip_atomic_fetch_add(p, v, __ATOMIC_RELAXED, __HIP_MEMORY_SCOPE_AGENT); }
; #define XB_SPIN(cond, bar) do { unsigned _sp = 0; while (cond) { __builtin_amdgcn_s_sleep(1); \
;     if ((++_sp & 255u) == 0u) { if (xb_ld(&(bar)[XB_TMO])) break; if (_sp > XB_SPIN_CAP) { atomicAdd(&(bar)[XB_TMO], 1u); break; } } } } while (0)
; __device__ __forceinline__ void xcd_barrier(const XcdBarrier& b) {
;     ...
;         const unsigned old = xb_add(&bar[XB_XSUB(b.x)], 1u);
;         const unsigned gen = old / nloc;
;         if (old + 1u == (gen + 1u) * nloc) {
;             __builtin_amdgcn_fence(__ATOMIC_RELEASE, "agent");
;             asm volatile("s_waitcnt vmcnt(0)" ::: "memory");
;             const unsigned og = xb_add(&bar[XB_TOP], 1u);
;             const unsigned tg = og / nx;
;             if (og + 1u == (tg + 1u) * nx) xb_add(&bar[XB_TOPGEN], 1u);
;             else XB_SPIN(xb_ld(&bar[XB_TOPGEN]) == tg, bar);
;             __builtin_amdgcn_fence(__ATOMIC_ACQUIRE, "agent");
;             xb_add(&bar[XB_XGEN(b.x)], 1u);
;             asm volatile("s_waitcnt vmcnt(0)" ::: "memory");
;         } else {
;             XB_SPIN(xb_ld(&bar[XB_XGEN(b.x)]) == gen, bar);
.LBB0_125:
	s_or_b64 exec, exec, s[14:15]
	v_cvt_f32_u32_e32 v4, v2
	s_waitcnt vmcnt(0)
	v_readfirstlane_b32 s3, v3
	v_sub_u32_e32 v3, 0, v2
	v_rcp_iflag_f32_e32 v4, v4
	v_add_u32_e32 v5, s3, v1
	v_mul_f32_e32 v4, 0x4f7ffffe, v4
	v_cvt_u32_f32_e32 v4, v4
	v_mul_lo_u32 v1, v3, v4
	v_mul_hi_u32 v1, v4, v1
	v_add_u32_e32 v1, v4, v1
	v_mul_hi_u32 v1, v5, v1
	v_mul_lo_u32 v3, v1, v2
	v_sub_u32_e32 v3, v5, v3
	v_add_u32_e32 v4, 1, v1
	v_cmp_ge_u32_e32 vcc, v3, v2
	s_nop 1
	v_cndmask_b32_e32 v1, v1, v4, vcc
	v_sub_u32_e32 v4, v3, v2
	v_cndmask_b32_e32 v3, v3, v4, vcc
	v_add_u32_e32 v4, 1, v1
	v_cmp_ge_u32_e32 vcc, v3, v2
	v_add_u32_e32 v3, 1, v5
	s_nop 0
	v_cndmask_b32_e32 v1, v1, v4, vcc
	v_mul_lo_u32 v4, v2, v1
	v_add_u32_e32 v2, v4, v2
	v_cmp_ne_u32_e32 vcc, v3, v2
	s_and_saveexec_b64 s[12:13], vcc
	s_xor_b64 s[12:13], exec, s[12:13]
	s_cbranch_execz .LBB0_139
	buffer_inv sc1
	s_waitcnt lgkmcnt(0)
	v_mov_b32_e32 v0, 0x2000
	global_load_dword v0, v0, s[10:11] offset:1024 sc1
	s_add_u32 s18, s10, 0x2400
	s_addc_u32 s19, s11, 0
	s_waitcnt vmcnt(0)
	v_cmp_eq_u32_e32 vcc, v0, v1
	s_and_saveexec_b64 s[14:15], vcc
	s_cbranch_execz .LBB0_138
	s_add_u32 s16, s26, 0x80200
	s_addc_u32 s17, s27, 0
	s_mov_b32 s3, 1
	s_mov_b64 s[20:21], 0
	v_mov_b32_e32 v0, 0
	s_branch .LBB0_129

; __device__ __forceinline__ unsigned xb_ld(unsigned* p)              { return __hip_atomic_load(p, __ATOMIC_RELAXED, __HIP_MEMORY_SCOPE_AGENT); }
; #define XB_SPIN(cond, bar) do { unsigned _sp = 0; while (cond) { __builtin_amdgcn_s_sleep(1); \
;     if ((++_sp & 255u) == 0u) { if (xb_ld(&(bar)[XB_TMO])) break; if (_sp > XB_SPIN_CAP) { atomicAdd(&(bar)[XB_TMO], 1u); break; } } } } while (0)
; __device__ __forceinline__ void xcd_barrier(const XcdBarrier& b) {
;     ...
;             XB_SPIN(xb_ld(&bar[XB_XGEN(b.x)]) == gen, bar);
;             __builtin_amdgcn_fence(__ATOMIC_ACQUIRE, "agent");
;             asm volatile("s_waitcnt vmcnt(0)" ::: "memory");
.LBB0_138:
	s_or_b64 exec, exec, s[14:15]
	s_waitcnt vmcnt(0)
	s_waitcnt vmcnt(0)

; __device__ __forceinline__ unsigned xb_ld(unsigned* p)              { return __hip_atomic_load(p, __ATOMIC_RELAXED, __HIP_MEMORY_SCOPE_AGENT); }
; __device__ __forceinline__ unsigned xb_add(unsigned* p, unsigned v) { return __hip_atomic_fetch_add(p, v, __ATOMIC_RELAXED, __HIP_MEMORY_SCOPE_AGENT); }
; #define XB_SPIN(cond, bar) do { unsigned _sp = 0; while (cond) { __builtin_amdgcn_s_sleep(1); \
;     if ((++_sp & 255u) == 0u) { if (xb_ld(&(bar)[XB_TMO])) break; if (_sp > XB_SPIN_CAP) { atomicAdd(&(bar)[XB_TMO], 1u); break; } } } } while (0)
; __device__ __forceinline__ void xcd_barrier(const XcdBarrier& b) {
;     ...
;         const unsigned old = xb_add(&bar[XB_XSUB(b.x)], 1u);
;         const unsigned gen = old / nloc;
;         if (old + 1u == (gen + 1u) * nloc) {
;             __builtin_amdgcn_fence(__ATOMIC_RELEASE, "agent");
;             asm volatile("s_waitcnt vmcnt(0)" ::: "memory");
;             const unsigned og = xb_add(&bar[XB_TOP], 1u);
;             const unsigned tg = og / nx;
;             if (og + 1u == (tg + 1u) * nx) xb_add(&bar[XB_TOPGEN], 1u);
;             else XB_SPIN(xb_ld(&bar[XB_TOPGEN]) == tg, bar);
;             __builtin_amdgcn_fence(__ATOMIC_ACQUIRE, "agent");
;             xb_add(&bar[XB_XGEN(b.x)], 1u);
;             asm volatile("s_waitcnt vmcnt(0)" ::: "memory");
;         } else {
;             XB_SPIN(xb_ld(&bar[XB_XGEN(b.x)]) == gen, bar);
.LBB0_793:
	s_or_b64 exec, exec, s[12:13]
	v_cvt_f32_u32_e32 v4, v2
	s_waitcnt vmcnt(0)
	v_readfirstlane_b32 s3, v3
	v_sub_u32_e32 v3, 0, v2
	v_rcp_iflag_f32_e32 v4, v4
	v_add_u32_e32 v5, s3, v1
	v_mul_f32_e32 v4, 0x4f7ffffe, v4
	v_cvt_u32_f32_e32 v4, v4
	v_mul_lo_u32 v1, v3, v4
	v_mul_hi_u32 v1, v4, v1
	v_add_u32_e32 v1, v4, v1
	v_mul_hi_u32 v1, v5, v1
	v_mul_lo_u32 v3, v1, v2
	v_sub_u32_e32 v3, v5, v3
	v_add_u32_e32 v4, 1, v1
	v_cmp_ge_u32_e32 vcc, v3, v2
	s_nop 1
	v_cndmask_b32_e32 v1, v1, v4, vcc
	v_sub_u32_e32 v4, v3, v2
	v_cndmask_b32_e32 v3, v3, v4, vcc
	v_add_u32_e32 v4, 1, v1
	v_cmp_ge_u32_e32 vcc, v3, v2
	v_add_u32_e32 v3, 1, v5
	s_nop 0
	v_cndmask_b32_e32 v1, v1, v4, vcc
	v_mul_lo_u32 v4, v2, v1
	v_add_u32_e32 v2, v4, v2
	v_cmp_ne_u32_e32 vcc, v3, v2
	s_and_saveexec_b64 s[10:11], vcc
	s_xor_b64 s[10:11], exec, s[10:11]
	s_cbranch_execz .LBB0_807
	buffer_inv sc1
	s_waitcnt lgkmcnt(0)
	v_mov_b32_e32 v0, 0x2000
	global_load_dword v0, v0, s[8:9] offset:1024 sc1
	s_add_u32 s16, s8, 0x2400
	s_addc_u32 s17, s9, 0
	s_waitcnt vmcnt(0)
	v_cmp_eq_u32_e32 vcc, v0, v1
	s_and_saveexec_b64 s[12:13], vcc
	s_cbranch_execz .LBB0_806
	s_add_u32 s14, s26, 0x80200
	s_addc_u32 s15, s27, 0
	s_mov_b32 s3, 1
	s_mov_b64 s[18:19], 0
	v_mov_b32_e32 v0, 0
	s_branch .LBB0_797

; __device__ __forceinline__ unsigned xb_ld(unsigned* p)              { return __hip_atomic_load(p, __ATOMIC_RELAXED, __HIP_MEMORY_SCOPE_AGENT); }
; #define XB_SPIN(cond, bar) do { unsigned _sp = 0; while (cond) { __builtin_amdgcn_s_sleep(1); \
;     if ((++_sp & 255u) == 0u) { if (xb_ld(&(bar)[XB_TMO])) break; if (_sp > XB_SPIN_CAP) { atomicAdd(&(bar)[XB_TMO], 1u); break; } } } } while (0)
; __device__ __forceinline__ void xcd_barrier(const XcdBarrier& b) {
;     ...
;             XB_SPIN(xb_ld(&bar[XB_XGEN(b.x)]) == gen, bar);
;             __builtin_amdgcn_fence(__ATOMIC_ACQUIRE, "agent");
;             asm volatile("s_waitcnt vmcnt(0)" ::: "memory");
.LBB0_806:
	s_or_b64 exec, exec, s[12:13]
	s_waitcnt vmcnt(0)
	s_waitcnt vmcnt(0)
